# scan pass 1 stage S3: value-product operand fragments read together behind counted LDS waits
# speedup vs baseline: 1.0023x; 1.0023x over previous
; #define LAS __attribute__((address_space(3)))
; #define MFMA32(a, b, c) __builtin_amdgcn_mfma_f32_32x32x16_bf16((a), (b), (c), 0, 0, 0)
; __device__ __forceinline__ void scan_pass1(const ScanP& sp, int b, int h, int seg, LAS unsigned char* lds) {
;     ...
;             if (isH) {
; #pragma unroll
;                 for (int ks = 0; ks < 2; ++ks) vfr[ks] = *(const LAS bf16x8*)(lds + O_VT + (icol * 40 + ks * 16 + hh * 8) * 2);
; #pragma unroll
;                 for (int ks = 0; ks < 2; ++ks) {
;                     P1 = MFMA32(*(const LAS bf16x8*)(lds + O_MK + (ln * 40 + ks * 16 + hh * 8) * 2), vfr[ks], P1);
;                     P2 = MFMA32(*(const LAS bf16x8*)(lds + O_NK + (ln * 40 + ks * 16 + hh * 8) * 2), vfr[ks], P2);
;                 }
.LBB0_304:
	s_andn2_b64 vcc, exec, s[0:1]
	v_or_b32_e32 v121, s82, v189
	s_cbranch_vccnz .LBB0_309
	v_mul_u32_u24_e32 v68, 0x50, v121
	s_movk_i32 s0, 0x50
	v_add3_u32 v68, 0, v113, v68
	v_mad_u32_u24 v72, v189, s0, v113
	s_add_i32 s0, 0, 0x10400
	s_add_i32 s1, 0, 0x10e00
	ds_read_b128 v[92:95], v68 offset:61440
	ds_read_b128 v[96:99], v68 offset:61472
	v_add_u32_e32 v230, s0, v72
	v_add_u32_e32 v231, s1, v72
	ds_read_b128 v[68:71], v230
	ds_read_b128 v[232:235], v231
	ds_read_b128 v[236:239], v230 offset:32
	ds_read_b128 v[240:243], v231 offset:32
	s_waitcnt lgkmcnt(3)
	v_mfma_f32_32x32x16_bf16 v[36:51], v[68:71], v[92:95], v[36:51]
	s_waitcnt lgkmcnt(2)
	v_mfma_f32_32x32x16_bf16 v[52:67], v[232:235], v[92:95], v[52:67]
	s_waitcnt lgkmcnt(1)
	v_mfma_f32_32x32x16_bf16 v[36:51], v[236:239], v[96:99], v[36:51]
	s_waitcnt lgkmcnt(0)
	v_mfma_f32_32x32x16_bf16 v[52:67], v[240:243], v[96:99], v[52:67]
	s_branch .LBB0_310

; #define LAS __attribute__((address_space(3)))
; #define MFMA32(a, b, c) __builtin_amdgcn_mfma_f32_32x32x16_bf16((a), (b), (c), 0, 0, 0)
; __device__ __forceinline__ void scan_pass1(const ScanP& sp, int b, int h, int seg, LAS unsigned char* lds) {
;     ...
;             f32x16 Aa;
; #pragma unroll
;             for (int i = 0; i < 16; ++i) Aa[i] = 0.f;
; #pragma unroll
;             for (int s = 0; s < 1; ++s) Aa = MFMA32(ld_krow(lds + O_TM + (ln * 40 + 4 * hh) * 2), pack8(P1, 0), Aa);
;             P1 = MFMA32(ld_krow(lds + O_N21 + (ln * 40 + 4 * hh) * 2), pack8(Aa, 0), P1);
;             Aa = MFMA32(ld_krow(lds + O_TM + (ln * 40 + 16 + 4 * hh) * 2), pack8(P1, 1), Aa);
;             bf16x8 ab[2]; ab[0] = pack8(Aa, 0); ab[1] = pack8(Aa, 1);
; #pragma unroll
;             for (int s = 0; s < 2; ++s) P2 = MFMA32(ld_krow(lds + O_NB + (ln * 40 + 16 * s + 4 * hh) * 2), ab[s], P2);
; #pragma unroll
;             for (int jb = 0; jb < 2; ++jb) {
;                 if (isH) {
; #pragma unroll
;                     for (int ks = 0; ks < 2; ++ks) Hacc[jb] = MFMA32(*(const LAS bf16x8*)(lds + O_KT + ((32 * jb + ln) * 40 + ks * 16 + hh * 8) * 2), vfr[ks], Hacc[jb]);
;                 }
; #pragma unroll
;                 for (int s = 0; s < 2; ++s) Hacc[jb] = MFMA32(ld_krow(lds + O_BT + ((32 * jb + ln) * 40 + 16 * s + 4 * hh) * 2), ab[s], Hacc[jb]);
.LBB0_310:
	v_lshlrev_b32_e32 v68, 3, v188
	s_add_i32 s0, 0, 0x11800
	v_add3_u32 v68, s0, v68, v112
	ds_read2_b64 v[68:71], v68 offset1:2
	v_lshlrev_b32_e32 v115, 2, v188
	v_mad_u32_u24 v123, v189, 40, v115
	v_lshlrev_b32_e32 v116, 1, v123
	v_add_u32_e32 v114, 0, v116
	v_cvt_pk_bf16_f32 v72, v36, v37
	v_cvt_pk_bf16_f32 v73, v38, v39
	v_cvt_pk_bf16_f32 v74, v40, v41
	v_cvt_pk_bf16_f32 v75, v42, v43
	v_add_u32_e32 v104, 0x1aa00, v114
	ds_read2_b64 v[104:107], v104 offset1:2
	s_waitcnt lgkmcnt(0)
	v_mfma_f32_32x32x16_bf16 v[68:83], v[68:71], v[72:75], 0
	v_add_u32_e32 v139, 0, v113
	v_cndmask_b32_e64 v113, 0, 1, s[54:55]
	s_andn2_b64 vcc, exec, s[54:55]
	s_nop 8
	v_cvt_pk_bf16_f32 v108, v68, v69
	v_cvt_pk_bf16_f32 v109, v70, v71
	v_cvt_pk_bf16_f32 v110, v72, v73
	v_cvt_pk_bf16_f32 v111, v74, v75
	s_nop 1
	v_mfma_f32_32x32x16_bf16 v[36:51], v[104:107], v[108:111], v[36:51]
	v_add_u32_e32 v104, s0, v116
	ds_read2_b64 v[104:107], v104 offset0:4 offset1:6
	v_cmp_ne_u32_e64 s[0:1], 1, v113
	s_nop 8
	v_cvt_pk_bf16_f32 v108, v44, v45
	v_cvt_pk_bf16_f32 v109, v46, v47
	v_cvt_pk_bf16_f32 v110, v48, v49
	v_cvt_pk_bf16_f32 v111, v50, v51
	s_waitcnt lgkmcnt(0)
	s_nop 0
	v_mfma_f32_32x32x16_bf16 v[68:83], v[104:107], v[108:111], v[68:83]
	v_add_u32_e32 v104, 0x12200, v114
	v_add_u32_e32 v108, 0x12220, v114
	ds_read2_b64 v[104:107], v104 offset1:2
	ds_read2_b64 v[108:111], v108 offset1:2
	s_cbranch_vccnz .LBB0_312
	v_add_u32_e32 v112, v139, v112
	ds_read_b128 v[116:119], v112 offset:51200
	ds_read_b128 v[244:247], v112 offset:51232
	s_waitcnt lgkmcnt(1)
	v_mfma_f32_32x32x16_bf16 v[20:35], v[116:119], v[92:95], v[20:35]
	s_waitcnt lgkmcnt(0)
	v_mfma_f32_32x32x16_bf16 v[20:35], v[244:247], v[96:99], v[20:35]
.LBB0_312:
	v_cvt_pk_bf16_f32 v68, v68, v69
	v_cvt_pk_bf16_f32 v69, v70, v71
	v_cvt_pk_bf16_f32 v70, v72, v73
	v_cvt_pk_bf16_f32 v71, v74, v75
	v_cvt_pk_bf16_f32 v72, v76, v77
	v_cvt_pk_bf16_f32 v74, v80, v81
	v_lshl_add_u32 v76, v115, 2, 0
	v_add_u32_e32 v80, 0xd800, v114
	v_cvt_pk_bf16_f32 v73, v78, v79
	v_cvt_pk_bf16_f32 v75, v82, v83
	v_add_u32_e32 v138, 0x13c00, v76
	ds_read2_b64 v[76:79], v80 offset0:128 offset1:130
	ds_read2_b64 v[80:83], v80 offset0:132 offset1:134
	s_waitcnt lgkmcnt(0)
	v_mfma_f32_32x32x16_bf16 v[20:35], v[76:79], v[68:71], v[20:35]
	s_and_b64 vcc, exec, s[0:1]
	v_mfma_f32_32x32x16_bf16 v[20:35], v[80:83], v[72:75], v[20:35]
	ds_read_b128 v[80:83], v138
	ds_read_b128 v[76:79], v138 offset:32
	ds_read_b128 v[112:115], v138 offset:64
	ds_read_b128 v[116:119], v138 offset:96
	s_cbranch_vccnz .LBB0_314
	v_or_b32_e32 v140, 32, v189
	s_movk_i32 s0, 0x50
	v_mad_u32_u24 v139, v140, s0, v139
	ds_read_b128 v[140:143], v139 offset:51200
	ds_read_b128 v[244:247], v139 offset:51232
	s_waitcnt lgkmcnt(1)
	v_mfma_f32_32x32x16_bf16 v[4:19], v[140:143], v[92:95], v[4:19]
	s_waitcnt lgkmcnt(0)
	v_mfma_f32_32x32x16_bf16 v[4:19], v[244:247], v[96:99], v[4:19]
